# P5/P6 tail units shared by two same-XCD workgroups split by wave half (inactive waves skip MFMAs, LDS fragment reads and epilogue); pp GEMM moved to WGs >= 32
# speedup vs baseline: 1.0794x; 1.0137x over previous
.Lp3_notpass2:
	s_abs_i32 s3, s70
	v_cvt_f32_u32_e32 v0, s3
	s_sub_i32 s4, 0, s3
	s_mov_b64 s[18:19], s[0:1]
	v_rcp_iflag_f32_e32 v0, v0
	s_nop 0
	v_mul_f32_e32 v0, 0x4f7ffffe, v0
	v_cvt_u32_f32_e32 v1, v0
	v_mov_b32_e32 v0, v174
	v_readfirstlane_b32 s5, v1
	s_mul_i32 s4, s4, s5
	s_mul_hi_u32 s4, s5, s4
	s_add_i32 s5, s5, s4
	s_mul_hi_u32 s4, s5, 0x110
	s_mul_i32 s4, s4, s3
	s_sub_i32 s4, 0x110, s4
	s_sub_i32 s5, s4, s3
	s_cmp_ge_u32 s4, s3
	s_cselect_b32 s4, s5, s4
	s_sub_i32 s5, s4, s3
	s_cmp_ge_u32 s4, s3
	s_cselect_b32 s3, s5, s4
	s_cmp_gt_i32 s70, 63
	s_cselect_b64 s[4:5], -1, 0
	s_cmp_lg_u32 s3, 0
	s_cselect_b64 s[8:9], -1, 0
	s_sub_i32 s10, s70, 32
	s_and_b64 s[4:5], s[4:5], s[8:9]
	s_cmp_lt_i32 s3, s10
	s_cselect_b64 s[8:9], -1, 0
	s_and_b64 s[4:5], s[4:5], s[8:9]
	s_and_b64 s[4:5], s[4:5], exec
	s_cselect_b32 s3, s3, 0
	s_cmp_eq_u32 s99, 1
	s_cselect_b32 s3, 0x60, 32
	s_cmp_ge_i32 s2, s3
	s_cselect_b64 s[16:17], -1, 0
	s_cmp_eq_u32 s99, 2
	s_cbranch_scc1 .LBB0_1768
	s_cmp_eq_u32 s99, 3
	s_cbranch_scc1 .Lp3_pass2_done
	s_cmp_lt_i32 s2, s3
	s_cbranch_scc1 .LBB0_1768
	s_waitcnt lgkmcnt(0)
	v_ashrrev_i32_e32 v2, 6, v0
	s_sub_i32 s4, s2, s3
	v_lshl_add_u32 v18, s4, 3, v2
	s_sub_i32 s4, s70, s3
	s_load_dwordx2 s[20:21], s[18:19], 0x128
	v_lshlrev_b32_e32 v15, 14, v2
	s_lshl_b32 s4, s4, 3
	v_ashrrev_i32_e32 v2, 31, v18
	v_and_b32_e32 v2, s4, v2
	v_and_b32_e32 v1, 63, v0
	v_add_u32_e32 v19, v2, v18
	s_movk_i32 s5, 0x580
	v_add_u32_e32 v16, 0, v15
	v_cmp_gt_i32_e32 vcc, s5, v19
	v_lshrrev_b32_e32 v4, 5, v1
	v_and_b32_e32 v5, 31, v0
	v_lshrrev_b32_e32 v14, 3, v1
	v_lshlrev_b32_e32 v17, 3, v1
	s_and_saveexec_b64 s[22:23], vcc
	s_cbranch_execz .LBB0_1587
	s_load_dwordx4 s[12:15], s[18:19], 0xe0
	v_and_b32_e32 v0, 56, v17
	v_mul_u32_u24_e32 v2, 0x84, v0
	v_lshlrev_b32_e32 v0, 1, v0
	v_mov_b32_e32 v1, 0
	s_waitcnt lgkmcnt(0)
	v_lshl_add_u64 v[0:1], s[20:21], 0, v[0:1]
	s_mov_b64 s[10:11], 0x1100000
	s_movk_i32 s5, 0x84
	s_cmp_lg_u64 s[12:13], 0
	v_lshl_add_u64 v[6:7], v[0:1], 0, s[10:11]
	v_lshlrev_b32_e32 v0, 2, v14
	s_cselect_b64 s[8:9], -1, 0
	v_add3_u32 v20, v16, v2, v0
	v_mad_u32_u24 v0, v4, s5, v15
	v_lshlrev_b32_e32 v1, 2, v5
	v_add3_u32 v24, v0, v1, 0
	s_add_u32 s26, s12, 56
	v_cndmask_b32_e64 v0, 0, 1, s[8:9]
	s_mov_b64 s[24:25], 0
	v_or_b32_e32 v21, 8, v14
	v_or_b32_e32 v22, 16, v14
	v_or_b32_e32 v23, 24, v14
	s_addc_u32 s27, s13, 0
	s_mov_b32 s5, 0x2e8ba2e9
	s_movk_i32 s30, 0x58
	s_movk_i32 s31, 0xb00
	s_movk_i32 s34, 0x2c00
	v_cmp_ne_u32_e64 s[8:9], 1, v0
	s_movk_i32 s35, 0x400
	s_movk_i32 s36, 0x67
	s_movk_i32 s37, 0x6f
	s_movk_i32 s38, 0x77
	s_movk_i32 s39, 0x7f
	s_movk_i32 s40, 0x57f
	s_branch .LBB0_1529

.LBB0_1897:
	s_add_i32 s49, s49, 1
	v_lshrrev_b32_e32 v244, 8, v174
	s_and_b32 s95, s2, 15
	v_readfirstlane_b32 s94, v244
	s_cmp_lt_u32 s2, 32
	s_cselect_b32 s95, s95, s2
	s_lshr_b32 s96, s2, 4
	s_cmp_lg_u32 s94, s96
	s_cselect_b32 s97, 1, 0
	s_cmp_eq_u32 s49, 2
	s_cselect_b32 s97, s97, 0
	s_cmp_lt_u32 s2, 32
	s_cselect_b32 s97, s97, 0
	s_mul_i32 s10, s49, s52
	s_mul_hi_u32 s11, s49, s53
	s_add_i32 s11, s11, s10
	s_mul_i32 s10, s49, s53
	s_add_u32 s10, s10, s95
	s_addc_u32 s11, s11, s54
	v_cmp_gt_i64_e32 vcc, s[10:11], v[144:145]
	v_cmp_lt_i64_e64 s[12:13], s[10:11], v[142:143]
	s_cbranch_vccnz .LBB0_1899
	s_ashr_i32 s11, s10, 31
	s_lshr_b32 s11, s11, 29
	s_add_i32 s11, s10, s11
	s_ashr_i32 s30, s11, 3
	s_and_b32 s11, s11, -8
	s_sub_i32 s10, s10, s11
	s_cmp_lt_i32 s10, 0
	s_cselect_b32 s11, 35, 34
	s_mul_i32 s10, s10, s11
	s_add_i32 s10, s10, s30
	s_ashr_i32 s11, s10, 31
	s_lshr_b32 s11, s11, 27
	s_add_i32 s11, s10, s11
	s_ashr_i32 s30, s11, 5
	s_lshl_b32 s30, s30, 3
	s_sub_i32 s31, 0x44, s30
	s_min_i32 s31, s31, 8
	s_abs_i32 s38, s31
	v_cvt_f32_u32_e32 v0, s38
	s_sub_i32 s40, 0, s38
	s_andn2_b32 s11, s11, 31
	s_sub_i32 s10, s10, s11
	v_rcp_iflag_f32_e32 v0, v0
	s_abs_i32 s11, s10
	s_xor_b32 s39, s10, s31
	s_ashr_i32 s39, s39, 31
	v_mul_f32_e32 v0, 0x4f7ffffe, v0
	v_cvt_u32_f32_e32 v0, v0
	s_nop 0
	v_readfirstlane_b32 s41, v0
	s_mul_i32 s40, s40, s41
	s_mul_hi_u32 s40, s41, s40
	s_add_i32 s41, s41, s40
	s_mul_hi_u32 s40, s11, s41
	s_mul_i32 s41, s40, s38
	s_sub_i32 s11, s11, s41
	s_add_i32 s62, s40, 1
	s_sub_i32 s41, s11, s38
	s_cmp_ge_u32 s11, s38
	s_cselect_b32 s40, s62, s40
	s_cselect_b32 s11, s41, s11
	s_add_i32 s41, s40, 1
	s_cmp_ge_u32 s11, s38
	s_cselect_b32 s11, s41, s40
	s_xor_b32 s11, s11, s39
	s_sub_i32 s62, s11, s39
	s_mul_i32 s11, s62, s31
	s_sub_i32 s10, s10, s11
	s_add_i32 s63, s30, s10

.LBB0_1904:
	s_cmp_eq_u32 s97, 1
	s_cbranch_scc1 .Lwhr_p5_0
	ds_read_b128 v[146:149], v157
	ds_read_b128 v[150:153], v157 offset:1024
	ds_read_b128 v[162:165], v157 offset:2048
	ds_read_b128 v[166:169], v157 offset:3072
	ds_read_b128 v[170:173], v158
	ds_read_b128 v[176:179], v158 offset:1024
	ds_read_b128 v[180:183], v158 offset:2048
	ds_read_b128 v[184:187], v158 offset:3072
.Lwhr_p5_0:
	s_add_u32 s36, s34, 0x100
	s_addc_u32 s37, s35, 0
	s_cmp_eq_u32 s73, 40
	s_cselect_b32 s41, s13, s37
	s_cselect_b32 s40, s12, s36
	s_cselect_b32 s39, s31, s72
	s_cselect_b32 s38, s30, s69
	v_lshl_add_u64 v[220:221], s[34:35], 0, v[138:139]
	s_add_i32 m0, s45, 0xc000
	s_cmp_eq_u32 s97, 1
	s_cbranch_scc1 .Lwhr_p5_1
	ds_read_b128 v[188:191], v159
	ds_read_b128 v[192:195], v159 offset:1024
	ds_read_b128 v[196:199], v159 offset:2048
	ds_read_b128 v[200:203], v159 offset:3072
	ds_read_b128 v[204:207], v159 offset:4096
	ds_read_b128 v[208:211], v159 offset:5120
	ds_read_b128 v[212:215], v159 offset:6144
	ds_read_b128 v[216:219], v159 offset:7168
.Lwhr_p5_1:
	global_load_lds_dwordx4 v[220:221], off
	v_lshl_add_u64 v[220:221], s[34:35], 0, v[140:141]
	s_add_i32 m0, s45, 0xe000
	s_nop 0
	global_load_lds_dwordx4 v[220:221], off
	s_waitcnt vmcnt(8)
	s_waitcnt lgkmcnt(0)
	s_barrier
	s_setprio 1
	s_cmp_eq_u32 s97, 1
	s_cbranch_scc1 .Lwh_p5_0
	s_waitcnt lgkmcnt(0)
	v_mfma_f32_16x16x32_bf16 v[124:127], v[146:149], v[188:191], v[124:127]
	v_mfma_f32_16x16x32_bf16 v[120:123], v[162:165], v[188:191], v[120:123]
	v_mfma_f32_16x16x32_bf16 v[108:111], v[146:149], v[196:199], v[108:111]
	v_mfma_f32_16x16x32_bf16 v[104:107], v[162:165], v[196:199], v[104:107]
	v_mfma_f32_16x16x32_bf16 v[92:95], v[146:149], v[204:207], v[92:95]
	v_mfma_f32_16x16x32_bf16 v[88:91], v[162:165], v[204:207], v[88:91]
	v_mfma_f32_16x16x32_bf16 v[76:79], v[146:149], v[212:215], v[76:79]
	v_mfma_f32_16x16x32_bf16 v[72:75], v[162:165], v[212:215], v[72:75]
	v_mfma_f32_16x16x32_bf16 v[124:127], v[150:153], v[192:195], v[124:127]
	v_mfma_f32_16x16x32_bf16 v[120:123], v[166:169], v[192:195], v[120:123]
	v_mfma_f32_16x16x32_bf16 v[108:111], v[150:153], v[200:203], v[108:111]
	v_mfma_f32_16x16x32_bf16 v[104:107], v[166:169], v[200:203], v[104:107]
	v_mfma_f32_16x16x32_bf16 v[92:95], v[150:153], v[208:211], v[92:95]
	v_mfma_f32_16x16x32_bf16 v[88:91], v[166:169], v[208:211], v[88:91]
	v_mfma_f32_16x16x32_bf16 v[76:79], v[150:153], v[216:219], v[76:79]
	v_mfma_f32_16x16x32_bf16 v[72:75], v[166:169], v[216:219], v[72:75]
.Lwh_p5_0:
	s_setprio 0
	s_setprio 1
	s_cmp_eq_u32 s97, 1
	s_cbranch_scc1 .Lwh_p5_1
	v_mfma_f32_16x16x32_bf16 v[116:119], v[170:173], v[188:191], v[116:119]
	v_mfma_f32_16x16x32_bf16 v[112:115], v[180:183], v[188:191], v[112:115]
	v_mfma_f32_16x16x32_bf16 v[100:103], v[170:173], v[196:199], v[100:103]
	v_mfma_f32_16x16x32_bf16 v[96:99], v[180:183], v[196:199], v[96:99]
	v_mfma_f32_16x16x32_bf16 v[84:87], v[170:173], v[204:207], v[84:87]
	v_mfma_f32_16x16x32_bf16 v[80:83], v[180:183], v[204:207], v[80:83]
	v_mfma_f32_16x16x32_bf16 v[68:71], v[170:173], v[212:215], v[68:71]
	v_mfma_f32_16x16x32_bf16 v[64:67], v[180:183], v[212:215], v[64:67]
	v_mfma_f32_16x16x32_bf16 v[116:119], v[176:179], v[192:195], v[116:119]
	v_mfma_f32_16x16x32_bf16 v[112:115], v[184:187], v[192:195], v[112:115]
	v_mfma_f32_16x16x32_bf16 v[100:103], v[176:179], v[200:203], v[100:103]
	v_mfma_f32_16x16x32_bf16 v[96:99], v[184:187], v[200:203], v[96:99]
	v_mfma_f32_16x16x32_bf16 v[84:87], v[176:179], v[208:211], v[84:87]
	v_mfma_f32_16x16x32_bf16 v[80:83], v[184:187], v[208:211], v[80:83]
	v_mfma_f32_16x16x32_bf16 v[68:71], v[176:179], v[216:219], v[68:71]
	v_mfma_f32_16x16x32_bf16 v[64:67], v[184:187], v[216:219], v[64:67]
.Lwh_p5_1:
	s_setprio 0
	s_barrier
	s_add_i32 s34, s55, s44
	v_lshl_add_u64 v[220:221], s[38:39], 0, v[130:131]
	s_mov_b32 m0, s34
	s_cmp_eq_u32 s97, 1
	s_cbranch_scc1 .Lwhr_p5_2
	ds_read_b128 v[188:191], v159 offset:16384
	ds_read_b128 v[192:195], v159 offset:17408
	ds_read_b128 v[196:199], v159 offset:18432
	ds_read_b128 v[200:203], v159 offset:19456
	ds_read_b128 v[204:207], v159 offset:20480
	ds_read_b128 v[208:211], v159 offset:21504
	ds_read_b128 v[212:215], v159 offset:22528
	ds_read_b128 v[216:219], v159 offset:23552
.Lwhr_p5_2:
	global_load_lds_dwordx4 v[220:221], off
	s_add_i32 m0, s34, 0x2000
	s_add_u32 s34, s38, 0xb0000
	v_lshl_add_u64 v[222:223], s[38:39], 0, v[134:135]
	s_addc_u32 s35, s39, 0
	s_add_i32 s74, s56, s44
	global_load_lds_dwordx4 v[222:223], off
	v_lshl_add_u64 v[224:225], s[34:35], 0, v[130:131]
	s_mov_b32 m0, s74
	v_lshl_add_u64 v[226:227], s[40:41], 0, v[132:133]
	global_load_lds_dwordx4 v[224:225], off
	v_lshl_add_u64 v[224:225], s[34:35], 0, v[134:135]
	s_add_i32 m0, s74, 0x2000
	s_nop 0
	global_load_lds_dwordx4 v[224:225], off
	v_lshl_add_u64 v[224:225], s[40:41], 0, v[128:129]
	s_mov_b32 m0, s45
	s_nop 0
	global_load_lds_dwordx4 v[224:225], off
	s_mov_b32 m0, s46
	s_nop 0
	global_load_lds_dwordx4 v[226:227], off
	s_waitcnt vmcnt(8)
	s_waitcnt lgkmcnt(0)
	s_barrier
	s_setprio 1
	s_cmp_eq_u32 s97, 1
	s_cbranch_scc1 .Lwh_p5_2
	s_waitcnt lgkmcnt(0)
	v_mfma_f32_16x16x32_bf16 v[60:63], v[146:149], v[188:191], v[60:63]
	v_mfma_f32_16x16x32_bf16 v[56:59], v[162:165], v[188:191], v[56:59]
	v_mfma_f32_16x16x32_bf16 v[44:47], v[146:149], v[196:199], v[44:47]
	v_mfma_f32_16x16x32_bf16 v[40:43], v[162:165], v[196:199], v[40:43]
	v_mfma_f32_16x16x32_bf16 v[28:31], v[146:149], v[204:207], v[28:31]
	v_mfma_f32_16x16x32_bf16 v[24:27], v[162:165], v[204:207], v[24:27]
	v_mfma_f32_16x16x32_bf16 v[12:15], v[146:149], v[212:215], v[12:15]
	v_mfma_f32_16x16x32_bf16 v[8:11], v[162:165], v[212:215], v[8:11]
	v_mfma_f32_16x16x32_bf16 v[60:63], v[150:153], v[192:195], v[60:63]
	v_mfma_f32_16x16x32_bf16 v[56:59], v[166:169], v[192:195], v[56:59]
	v_mfma_f32_16x16x32_bf16 v[44:47], v[150:153], v[200:203], v[44:47]
	v_mfma_f32_16x16x32_bf16 v[40:43], v[166:169], v[200:203], v[40:43]
	v_mfma_f32_16x16x32_bf16 v[28:31], v[150:153], v[208:211], v[28:31]
	v_mfma_f32_16x16x32_bf16 v[24:27], v[166:169], v[208:211], v[24:27]
	v_mfma_f32_16x16x32_bf16 v[12:15], v[150:153], v[216:219], v[12:15]
	v_mfma_f32_16x16x32_bf16 v[8:11], v[166:169], v[216:219], v[8:11]
.Lwh_p5_2:
	s_setprio 0
	s_setprio 1
	s_cmp_eq_u32 s97, 1
	s_cbranch_scc1 .Lwh_p5_3
	v_mfma_f32_16x16x32_bf16 v[52:55], v[170:173], v[188:191], v[52:55]
	v_mfma_f32_16x16x32_bf16 v[48:51], v[180:183], v[188:191], v[48:51]
	v_mfma_f32_16x16x32_bf16 v[36:39], v[170:173], v[196:199], v[36:39]
	v_mfma_f32_16x16x32_bf16 v[32:35], v[180:183], v[196:199], v[32:35]
	v_mfma_f32_16x16x32_bf16 v[20:23], v[170:173], v[204:207], v[20:23]
	v_mfma_f32_16x16x32_bf16 v[16:19], v[180:183], v[204:207], v[16:19]
	v_mfma_f32_16x16x32_bf16 v[4:7], v[170:173], v[212:215], v[4:7]
	v_mfma_f32_16x16x32_bf16 v[0:3], v[180:183], v[212:215], v[0:3]
	v_mfma_f32_16x16x32_bf16 v[52:55], v[176:179], v[192:195], v[52:55]
	v_mfma_f32_16x16x32_bf16 v[48:51], v[184:187], v[192:195], v[48:51]
	v_mfma_f32_16x16x32_bf16 v[36:39], v[176:179], v[200:203], v[36:39]
	v_mfma_f32_16x16x32_bf16 v[32:35], v[184:187], v[200:203], v[32:35]
	v_mfma_f32_16x16x32_bf16 v[20:23], v[176:179], v[208:211], v[20:23]
	v_mfma_f32_16x16x32_bf16 v[16:19], v[184:187], v[208:211], v[16:19]
	v_mfma_f32_16x16x32_bf16 v[4:7], v[176:179], v[216:219], v[4:7]
	v_mfma_f32_16x16x32_bf16 v[0:3], v[184:187], v[216:219], v[0:3]
.Lwh_p5_3:
	s_setprio 0
	s_barrier
	s_add_i32 s74, 0, 0x18000
	v_add_u32_e32 v136, s74, v155
	s_add_i32 s75, 0, 0x1c000
	s_cmp_eq_u32 s97, 1
	s_cbranch_scc1 .Lwhr_p5_3
	ds_read_b128 v[146:149], v136
	ds_read_b128 v[150:153], v136 offset:1024
	ds_read_b128 v[162:165], v136 offset:2048
	ds_read_b128 v[166:169], v136 offset:3072
.Lwhr_p5_3:
	v_add_u32_e32 v136, s75, v155
	s_cmp_eq_u32 s97, 1
	s_cbranch_scc1 .Lwhr_p5_4
	ds_read_b128 v[170:173], v136
	ds_read_b128 v[176:179], v136 offset:1024
	ds_read_b128 v[180:183], v136 offset:2048
	ds_read_b128 v[184:187], v136 offset:3072
.Lwhr_p5_4:
	s_add_u32 s34, s40, 0xb0000
	s_addc_u32 s35, s41, 0
	s_mov_b32 m0, s47
	v_lshl_add_u64 v[228:229], s[34:35], 0, v[128:129]
	s_cmp_eq_u32 s97, 1
	s_cbranch_scc1 .Lwhr_p5_5
	ds_read_b128 v[188:191], v159 offset:32768
	ds_read_b128 v[192:195], v159 offset:33792
	ds_read_b128 v[196:199], v159 offset:34816
	ds_read_b128 v[200:203], v159 offset:35840
	ds_read_b128 v[204:207], v159 offset:36864
	ds_read_b128 v[208:211], v159 offset:37888
	ds_read_b128 v[212:215], v159 offset:38912
	ds_read_b128 v[216:219], v159 offset:39936
.Lwhr_p5_5:
	global_load_lds_dwordx4 v[228:229], off
	v_lshl_add_u64 v[228:229], s[34:35], 0, v[132:133]
	s_mov_b32 m0, s48
	s_nop 0
	global_load_lds_dwordx4 v[228:229], off
	s_waitcnt vmcnt(8)
	s_waitcnt lgkmcnt(0)
	s_barrier
	s_setprio 1
	s_cmp_eq_u32 s97, 1
	s_cbranch_scc1 .Lwh_p5_4
	s_waitcnt lgkmcnt(0)
	v_mfma_f32_16x16x32_bf16 v[124:127], v[146:149], v[188:191], v[124:127]
	v_mfma_f32_16x16x32_bf16 v[120:123], v[162:165], v[188:191], v[120:123]
	v_mfma_f32_16x16x32_bf16 v[108:111], v[146:149], v[196:199], v[108:111]
	v_mfma_f32_16x16x32_bf16 v[104:107], v[162:165], v[196:199], v[104:107]
	v_mfma_f32_16x16x32_bf16 v[92:95], v[146:149], v[204:207], v[92:95]
	v_mfma_f32_16x16x32_bf16 v[88:91], v[162:165], v[204:207], v[88:91]
	v_mfma_f32_16x16x32_bf16 v[76:79], v[146:149], v[212:215], v[76:79]
	v_mfma_f32_16x16x32_bf16 v[72:75], v[162:165], v[212:215], v[72:75]
	v_mfma_f32_16x16x32_bf16 v[124:127], v[150:153], v[192:195], v[124:127]
	v_mfma_f32_16x16x32_bf16 v[120:123], v[166:169], v[192:195], v[120:123]
	v_mfma_f32_16x16x32_bf16 v[108:111], v[150:153], v[200:203], v[108:111]
	v_mfma_f32_16x16x32_bf16 v[104:107], v[166:169], v[200:203], v[104:107]
	v_mfma_f32_16x16x32_bf16 v[92:95], v[150:153], v[208:211], v[92:95]
	v_mfma_f32_16x16x32_bf16 v[88:91], v[166:169], v[208:211], v[88:91]
	v_mfma_f32_16x16x32_bf16 v[76:79], v[150:153], v[216:219], v[76:79]
	v_mfma_f32_16x16x32_bf16 v[72:75], v[166:169], v[216:219], v[72:75]

.Lwh_p5_5:
	s_setprio 0
	s_barrier
	s_add_i32 s34, s74, s44
	v_lshl_add_u64 v[220:221], v[220:221], 0, s[26:27]
	s_mov_b32 m0, s34
	s_cmp_eq_u32 s97, 1
	s_cbranch_scc1 .Lwhr_p5_6
	ds_read_b128 v[188:191], v159 offset:49152
	ds_read_b128 v[192:195], v159 offset:50176
	ds_read_b128 v[196:199], v159 offset:51200
	ds_read_b128 v[200:203], v159 offset:52224
	ds_read_b128 v[204:207], v159 offset:53248
	ds_read_b128 v[208:211], v159 offset:54272
	ds_read_b128 v[212:215], v159 offset:55296
	ds_read_b128 v[216:219], v159 offset:56320
.Lwhr_p5_6:
	global_load_lds_dwordx4 v[220:221], off
	s_add_i32 m0, s34, 0x2000
	s_add_u32 s34, s38, 0xb0080
	v_lshl_add_u64 v[220:221], v[222:223], 0, s[26:27]
	s_addc_u32 s35, s39, 0
	s_add_i32 s38, s75, s44
	global_load_lds_dwordx4 v[220:221], off
	v_lshl_add_u64 v[220:221], s[34:35], 0, v[130:131]
	s_mov_b32 m0, s38
	s_nop 0
	global_load_lds_dwordx4 v[220:221], off
	v_lshl_add_u64 v[220:221], s[34:35], 0, v[134:135]
	s_add_i32 m0, s38, 0x2000
	s_nop 0
	global_load_lds_dwordx4 v[220:221], off
	v_lshl_add_u64 v[220:221], v[224:225], 0, s[26:27]
	s_mov_b32 m0, s50
	s_nop 0
	global_load_lds_dwordx4 v[220:221], off
	v_lshl_add_u64 v[220:221], v[226:227], 0, s[26:27]
	s_mov_b32 m0, s51
	s_nop 0
	global_load_lds_dwordx4 v[220:221], off
	s_waitcnt vmcnt(8)
	s_waitcnt lgkmcnt(0)
	s_barrier
	s_setprio 1
	s_cmp_eq_u32 s97, 1
	s_cbranch_scc1 .Lwh_p5_6
	s_waitcnt lgkmcnt(0)
	v_mfma_f32_16x16x32_bf16 v[60:63], v[146:149], v[188:191], v[60:63]
	v_mfma_f32_16x16x32_bf16 v[56:59], v[162:165], v[188:191], v[56:59]
	v_mfma_f32_16x16x32_bf16 v[44:47], v[146:149], v[196:199], v[44:47]
	v_mfma_f32_16x16x32_bf16 v[40:43], v[162:165], v[196:199], v[40:43]
	v_mfma_f32_16x16x32_bf16 v[28:31], v[146:149], v[204:207], v[28:31]
	v_mfma_f32_16x16x32_bf16 v[24:27], v[162:165], v[204:207], v[24:27]
	v_mfma_f32_16x16x32_bf16 v[12:15], v[146:149], v[212:215], v[12:15]
	v_mfma_f32_16x16x32_bf16 v[8:11], v[162:165], v[212:215], v[8:11]
	v_mfma_f32_16x16x32_bf16 v[60:63], v[150:153], v[192:195], v[60:63]
	v_mfma_f32_16x16x32_bf16 v[56:59], v[166:169], v[192:195], v[56:59]
	v_mfma_f32_16x16x32_bf16 v[44:47], v[150:153], v[200:203], v[44:47]
	v_mfma_f32_16x16x32_bf16 v[40:43], v[166:169], v[200:203], v[40:43]
	v_mfma_f32_16x16x32_bf16 v[28:31], v[150:153], v[208:211], v[28:31]
	v_mfma_f32_16x16x32_bf16 v[24:27], v[166:169], v[208:211], v[24:27]
	v_mfma_f32_16x16x32_bf16 v[12:15], v[150:153], v[216:219], v[12:15]
	v_mfma_f32_16x16x32_bf16 v[8:11], v[166:169], v[216:219], v[8:11]

.Lwh_p5_7:
	s_setprio 0
	s_barrier
	s_add_i32 s73, s73, 2
	s_add_u32 s69, s69, 0x100
	s_addc_u32 s72, s72, 0
	s_cmp_gt_u32 s73, 41
	s_mov_b64 s[34:35], s[36:37]
	s_cbranch_scc0 .LBB0_1904
	s_and_b64 vcc, exec, s[28:29]
	s_cbranch_vccz .LBB0_1907
	s_barrier
.LBB0_1907:
	s_cmp_eq_u32 s97, 1
	s_cbranch_scc1 .Lwh_p5_epi
	v_lshl_add_u32 v150, s68, 8, v154
	v_cmp_lt_i32_e32 vcc, s57, v150
	s_and_saveexec_b64 s[34:35], vcc
	s_xor_b64 s[34:35], exec, s[34:35]
	v_add_u32_e32 v136, 0xffffc000, v150
	v_lshlrev_b64 v[146:147], 12, v[136:137]
	v_lshl_add_u64 v[152:153], s[20:21], 0, v[146:147]
	v_mov_b32_e32 v151, v137
	s_andn2_saveexec_b64 s[34:35], s[34:35]
	v_ashrrev_i32_e32 v151, 31, v150
	v_lshlrev_b64 v[146:147], 12, v[150:151]
	v_lshl_add_u64 v[152:153], s[18:19], 0, v[146:147]
	s_or_b64 exec, exec, s[34:35]
	v_lshl_or_b32 v146, s65, 8, v156
	v_ashrrev_i32_e32 v147, 31, v146
	v_lshlrev_b64 v[148:149], 2, v[146:147]
	v_lshl_add_u64 v[152:153], v[152:153], 0, v[148:149]
	global_load_dwordx4 v[162:165], v[152:153], off
	global_load_dwordx4 v[166:169], v[152:153], off offset:16
	v_lshlrev_b64 v[170:171], 12, v[150:151]
	v_lshlrev_b64 v[172:173], 11, v[150:151]
	v_lshl_add_u64 v[170:171], s[18:19], 0, v[170:171]
	v_lshl_add_u64 v[172:173], s[22:23], 0, v[172:173]
	v_lshl_add_u64 v[176:177], v[146:147], 1, v[172:173]
	v_lshl_add_u64 v[178:179], v[170:171], 0, v[148:149]
	v_xor_b32_e32 v136, 32, v160
	s_waitcnt vmcnt(0)
	v_pk_add_f32 v[126:127], v[126:127], v[164:165]
	v_pk_add_f32 v[124:125], v[124:125], v[162:163]
	v_pk_add_f32 v[164:165], v[122:123], v[168:169]
	v_pk_add_f32 v[162:163], v[120:121], v[166:167]
	global_store_dwordx4 v[178:179], v[124:127], off
	global_store_dwordx4 v[178:179], v[162:165], off offset:16
	v_cvt_pk_bf16_f32 v120, v124, v125
	v_cvt_pk_bf16_f32 v121, v126, v127
	v_cvt_pk_bf16_f32 v122, v162, v163
	v_cvt_pk_bf16_f32 v123, v164, v165
	global_store_dwordx4 v[176:177], v[120:123], off
	global_load_dwordx4 v[166:169], v[152:153], off offset:512
	global_load_dwordx4 v[170:173], v[152:153], off offset:528
	v_mul_f32_e32 v122, v125, v125
	v_mul_f32_e32 v123, v127, v127
	v_mul_f32_e32 v125, v163, v163
	v_mul_f32_e32 v127, v165, v165
	v_fmac_f32_e32 v122, v124, v124
	v_fmac_f32_e32 v123, v126, v126
	v_fmac_f32_e32 v125, v162, v162
	v_fmac_f32_e32 v127, v164, v164
	v_add_f32_e32 v122, v122, v123
	v_add_f32_e32 v123, v125, v127
	v_add_f32_e32 v126, v122, v123
	v_and_b32_e32 v121, 64, v160
	v_xor_b32_e32 v120, 16, v160
	v_add_u32_e32 v121, 64, v121
	v_cmp_lt_i32_e32 vcc, v120, v121
	s_waitcnt vmcnt(1)
	v_pk_add_f32 v[118:119], v[118:119], v[168:169]
	v_pk_add_f32 v[116:117], v[116:117], v[166:167]
	s_waitcnt vmcnt(0)
	v_pk_add_f32 v[124:125], v[114:115], v[172:173]
	v_pk_add_f32 v[122:123], v[112:113], v[170:171]
	v_mul_f32_e32 v112, v117, v117
	v_mul_f32_e32 v113, v119, v119
	v_mul_f32_e32 v114, v123, v123
	v_mul_f32_e32 v115, v125, v125
	v_fmac_f32_e32 v112, v116, v116
	v_fmac_f32_e32 v113, v118, v118
	v_fmac_f32_e32 v114, v122, v122
	v_fmac_f32_e32 v115, v124, v124
	v_add_f32_e32 v112, v112, v113
	v_add_f32_e32 v113, v114, v115
	v_cndmask_b32_e32 v120, v160, v120, vcc
	v_add_f32_e32 v112, v112, v113
	v_lshlrev_b32_e32 v120, 2, v120
	v_add_f32_e32 v112, v126, v112
	ds_bpermute_b32 v113, v120, v112
	v_cmp_lt_i32_e32 vcc, v136, v121
	global_store_dwordx4 v[178:179], v[116:119], off offset:512
	global_store_dwordx4 v[178:179], v[122:125], off offset:528
	v_cndmask_b32_e32 v114, v160, v136, vcc
	v_cvt_pk_bf16_f32 v162, v116, v117
	s_waitcnt lgkmcnt(0)
	v_add_f32_e32 v112, v112, v113
	v_lshlrev_b32_e32 v116, 2, v114
	ds_bpermute_b32 v113, v116, v112
	v_cvt_pk_bf16_f32 v163, v118, v119
	v_cvt_pk_bf16_f32 v164, v122, v123
	v_cvt_pk_bf16_f32 v165, v124, v125
	global_store_dwordx4 v[176:177], v[162:165], off offset:256
	s_and_saveexec_b64 s[34:35], s[8:9]
	s_cbranch_execz .LBB0_1913
	s_waitcnt lgkmcnt(0)
	v_add_f32_e32 v112, v112, v113
	v_mul_f32_e32 v112, 0x49800000, v112
	v_trunc_f32_e32 v112, v112
	v_mul_f32_e32 v113, 0x2f800000, v112
	v_floor_f32_e32 v113, v113
	v_fmac_f32_e32 v112, 0xcf800000, v113
	v_cvt_u32_f32_e32 v112, v112
	v_cvt_u32_f32_e32 v113, v113
	v_lshl_add_u64 v[114:115], v[150:151], 3, s[24:25]
	global_atomic_add_x2 v[114:115], v[112:113], off

.Lwh_p5_epi:
	s_and_b64 vcc, exec, s[10:11]
	s_mov_b64 s[10:11], -1
	s_cbranch_vccnz .LBB0_1896
	s_andn2_b64 vcc, exec, s[14:15]
	s_cbranch_vccnz .LBB0_1895
	s_barrier
	s_branch .LBB0_1895

.LBB0_2037:
	s_add_i32 s49, s49, 1
	v_lshrrev_b32_e32 v244, 8, v174
	s_and_b32 s95, s2, 15
	v_readfirstlane_b32 s94, v244
	s_cmp_lt_u32 s2, 32
	s_cselect_b32 s95, s95, s2
	s_lshr_b32 s96, s2, 4
	s_cmp_lg_u32 s94, s96
	s_cselect_b32 s97, 1, 0
	s_cmp_eq_u32 s49, 2
	s_cselect_b32 s97, s97, 0
	s_cmp_lt_u32 s2, 32
	s_cselect_b32 s97, s97, 0
	s_mul_i32 s8, s49, s52
	s_mul_hi_u32 s9, s49, s53
	s_add_i32 s9, s9, s8
	s_mul_i32 s8, s49, s53
	s_add_u32 s28, s8, s95
	s_addc_u32 s29, s9, s54
	v_cmp_gt_i64_e32 vcc, s[28:29], v[142:143]
	v_cmp_lt_i64_e64 s[8:9], s[28:29], v[140:141]
	s_cbranch_vccnz .LBB0_2039
	s_ashr_i32 s24, s28, 31
	s_lshr_b32 s24, s24, 29
	s_add_i32 s24, s28, s24
	s_ashr_i32 s25, s24, 3
	s_and_b32 s24, s24, -8
	s_sub_i32 s24, s28, s24
	s_cmp_lt_i32 s24, 0
	s_cselect_b32 s26, 35, 34
	s_mul_i32 s24, s24, s26
	s_add_i32 s24, s24, s25
	s_ashr_i32 s25, s24, 31
	s_lshr_b32 s25, s25, 27
	s_add_i32 s25, s24, s25
	s_ashr_i32 s26, s25, 5
	s_lshl_b32 s26, s26, 3
	s_sub_i32 s27, 0x44, s26
	s_min_i32 s27, s27, 8
	s_abs_i32 s28, s27
	v_cvt_f32_u32_e32 v0, s28
	s_sub_i32 s30, 0, s28
	s_andn2_b32 s25, s25, 31
	s_sub_i32 s25, s24, s25
	v_rcp_iflag_f32_e32 v0, v0
	s_abs_i32 s24, s25
	s_xor_b32 s29, s25, s27
	s_ashr_i32 s29, s29, 31
	v_mul_f32_e32 v0, 0x4f7ffffe, v0
	v_cvt_u32_f32_e32 v0, v0
	s_nop 0
	v_readfirstlane_b32 s31, v0
	s_mul_i32 s30, s30, s31
	s_mul_hi_u32 s30, s31, s30
	s_add_i32 s31, s31, s30
	s_mul_hi_u32 s30, s24, s31
	s_mul_i32 s31, s30, s28
	s_sub_i32 s24, s24, s31
	s_add_i32 s35, s30, 1
	s_sub_i32 s31, s24, s28
	s_cmp_ge_u32 s24, s28
	s_cselect_b32 s30, s35, s30
	s_cselect_b32 s24, s31, s24
	s_add_i32 s31, s30, 1
	s_cmp_ge_u32 s24, s28
	s_cselect_b32 s24, s31, s30
	s_xor_b32 s24, s24, s29
	s_sub_i32 s24, s24, s29
	s_mul_i32 s27, s24, s27
	s_sub_i32 s25, s25, s27
	s_add_i32 s26, s26, s25

.LBB0_2040:
	s_cmp_eq_u32 s97, 1
	s_cbranch_scc1 .Lwhr_p6_0
	ds_read_b128 v[144:147], v155
	ds_read_b128 v[148:151], v155 offset:1024
	ds_read_b128 v[160:163], v155 offset:2048
	ds_read_b128 v[164:167], v155 offset:3072
	ds_read_b128 v[168:171], v156
	ds_read_b128 v[176:179], v156 offset:1024
	ds_read_b128 v[180:183], v156 offset:2048
	ds_read_b128 v[184:187], v156 offset:3072
.Lwhr_p6_0:
	s_add_u32 s40, s38, 0xfffc0080
	s_addc_u32 s41, s39, -1
	s_cmp_eq_u32 s61, 12
	s_cselect_b32 s43, s27, s41
	s_cselect_b32 s42, s35, s40
	s_cselect_b32 s41, s25, s60
	s_cselect_b32 s40, s58, s59
	v_lshl_add_u64 v[172:173], s[38:39], 0, v[136:137]
	s_add_i32 m0, s37, 0xc000
	s_cmp_eq_u32 s97, 1
	s_cbranch_scc1 .Lwhr_p6_1
	ds_read_b128 v[188:191], v157
	ds_read_b128 v[192:195], v157 offset:1024
	ds_read_b128 v[196:199], v157 offset:2048
	ds_read_b128 v[200:203], v157 offset:3072
	ds_read_b128 v[204:207], v157 offset:4096
	ds_read_b128 v[208:211], v157 offset:5120
	ds_read_b128 v[212:215], v157 offset:6144
	ds_read_b128 v[216:219], v157 offset:7168
.Lwhr_p6_1:
	global_load_lds_dwordx4 v[172:173], off
	v_lshl_add_u64 v[172:173], s[38:39], 0, v[138:139]
	s_add_i32 m0, s37, 0xe000
	s_nop 0
	global_load_lds_dwordx4 v[172:173], off
	s_waitcnt vmcnt(8)
	s_waitcnt lgkmcnt(0)
	s_barrier
	s_setprio 1
	s_cmp_eq_u32 s97, 1
	s_cbranch_scc1 .Lwh_p6_0
	s_waitcnt lgkmcnt(0)
	v_mfma_f32_16x16x32_bf16 v[124:127], v[144:147], v[188:191], v[124:127]
	v_mfma_f32_16x16x32_bf16 v[120:123], v[160:163], v[188:191], v[120:123]
	v_mfma_f32_16x16x32_bf16 v[108:111], v[144:147], v[196:199], v[108:111]
	v_mfma_f32_16x16x32_bf16 v[104:107], v[160:163], v[196:199], v[104:107]
	v_mfma_f32_16x16x32_bf16 v[92:95], v[144:147], v[204:207], v[92:95]
	v_mfma_f32_16x16x32_bf16 v[88:91], v[160:163], v[204:207], v[88:91]
	v_mfma_f32_16x16x32_bf16 v[76:79], v[144:147], v[212:215], v[76:79]
	v_mfma_f32_16x16x32_bf16 v[72:75], v[160:163], v[212:215], v[72:75]
	v_mfma_f32_16x16x32_bf16 v[124:127], v[148:151], v[192:195], v[124:127]
	v_mfma_f32_16x16x32_bf16 v[120:123], v[164:167], v[192:195], v[120:123]
	v_mfma_f32_16x16x32_bf16 v[108:111], v[148:151], v[200:203], v[108:111]
	v_mfma_f32_16x16x32_bf16 v[104:107], v[164:167], v[200:203], v[104:107]
	v_mfma_f32_16x16x32_bf16 v[92:95], v[148:151], v[208:211], v[92:95]
	v_mfma_f32_16x16x32_bf16 v[88:91], v[164:167], v[208:211], v[88:91]
	v_mfma_f32_16x16x32_bf16 v[76:79], v[148:151], v[216:219], v[76:79]
	v_mfma_f32_16x16x32_bf16 v[72:75], v[164:167], v[216:219], v[72:75]
.Lwh_p6_0:
	s_setprio 0
	s_setprio 1
	s_cmp_eq_u32 s97, 1
	s_cbranch_scc1 .Lwh_p6_1
	v_mfma_f32_16x16x32_bf16 v[116:119], v[168:171], v[188:191], v[116:119]
	v_mfma_f32_16x16x32_bf16 v[112:115], v[180:183], v[188:191], v[112:115]
	v_mfma_f32_16x16x32_bf16 v[100:103], v[168:171], v[196:199], v[100:103]
	v_mfma_f32_16x16x32_bf16 v[96:99], v[180:183], v[196:199], v[96:99]
	v_mfma_f32_16x16x32_bf16 v[84:87], v[168:171], v[204:207], v[84:87]
	v_mfma_f32_16x16x32_bf16 v[80:83], v[180:183], v[204:207], v[80:83]
	v_mfma_f32_16x16x32_bf16 v[68:71], v[168:171], v[212:215], v[68:71]
	v_mfma_f32_16x16x32_bf16 v[64:67], v[180:183], v[212:215], v[64:67]
	v_mfma_f32_16x16x32_bf16 v[116:119], v[176:179], v[192:195], v[116:119]
	v_mfma_f32_16x16x32_bf16 v[112:115], v[184:187], v[192:195], v[112:115]
	v_mfma_f32_16x16x32_bf16 v[100:103], v[176:179], v[200:203], v[100:103]
	v_mfma_f32_16x16x32_bf16 v[96:99], v[184:187], v[200:203], v[96:99]
	v_mfma_f32_16x16x32_bf16 v[84:87], v[176:179], v[208:211], v[84:87]
	v_mfma_f32_16x16x32_bf16 v[80:83], v[184:187], v[208:211], v[80:83]
	v_mfma_f32_16x16x32_bf16 v[68:71], v[176:179], v[216:219], v[68:71]
	v_mfma_f32_16x16x32_bf16 v[64:67], v[184:187], v[216:219], v[64:67]
.Lwh_p6_1:
	s_setprio 0
	s_barrier
	s_add_i32 s62, s55, s45
	v_lshl_add_u64 v[172:173], s[40:41], 0, v[130:131]
	s_mov_b32 m0, s62
	s_cmp_eq_u32 s97, 1
	s_cbranch_scc1 .Lwhr_p6_2
	ds_read_b128 v[188:191], v157 offset:16384
	ds_read_b128 v[192:195], v157 offset:17408
	ds_read_b128 v[196:199], v157 offset:18432
	ds_read_b128 v[200:203], v157 offset:19456
	ds_read_b128 v[204:207], v157 offset:20480
	ds_read_b128 v[208:211], v157 offset:21504
	ds_read_b128 v[212:215], v157 offset:22528
	ds_read_b128 v[216:219], v157 offset:23552
.Lwhr_p6_2:
	global_load_lds_dwordx4 v[172:173], off
	s_add_i32 m0, s62, 0x2000
	s_add_u32 s62, s40, 0x40000
	v_lshl_add_u64 v[220:221], s[40:41], 0, v[134:135]
	s_addc_u32 s63, s41, 0
	s_add_i32 s65, s56, s45
	global_load_lds_dwordx4 v[220:221], off
	v_lshl_add_u64 v[222:223], s[62:63], 0, v[130:131]
	s_mov_b32 m0, s65
	v_lshl_add_u64 v[224:225], s[42:43], 0, v[132:133]
	global_load_lds_dwordx4 v[222:223], off
	v_lshl_add_u64 v[222:223], s[62:63], 0, v[134:135]
	s_add_i32 m0, s65, 0x2000
	s_nop 0
	global_load_lds_dwordx4 v[222:223], off
	v_lshl_add_u64 v[222:223], s[42:43], 0, v[128:129]
	s_mov_b32 m0, s37
	s_nop 0
	global_load_lds_dwordx4 v[222:223], off
	s_mov_b32 m0, s46
	s_nop 0
	global_load_lds_dwordx4 v[224:225], off
	s_waitcnt vmcnt(8)
	s_waitcnt lgkmcnt(0)
	s_barrier
	s_setprio 1
	s_cmp_eq_u32 s97, 1
	s_cbranch_scc1 .Lwh_p6_2
	s_waitcnt lgkmcnt(0)
	v_mfma_f32_16x16x32_bf16 v[60:63], v[144:147], v[188:191], v[60:63]
	v_mfma_f32_16x16x32_bf16 v[56:59], v[160:163], v[188:191], v[56:59]
	v_mfma_f32_16x16x32_bf16 v[44:47], v[144:147], v[196:199], v[44:47]
	v_mfma_f32_16x16x32_bf16 v[40:43], v[160:163], v[196:199], v[40:43]
	v_mfma_f32_16x16x32_bf16 v[28:31], v[144:147], v[204:207], v[28:31]
	v_mfma_f32_16x16x32_bf16 v[24:27], v[160:163], v[204:207], v[24:27]
	v_mfma_f32_16x16x32_bf16 v[12:15], v[144:147], v[212:215], v[12:15]
	v_mfma_f32_16x16x32_bf16 v[8:11], v[160:163], v[212:215], v[8:11]
	v_mfma_f32_16x16x32_bf16 v[60:63], v[148:151], v[192:195], v[60:63]
	v_mfma_f32_16x16x32_bf16 v[56:59], v[164:167], v[192:195], v[56:59]
	v_mfma_f32_16x16x32_bf16 v[44:47], v[148:151], v[200:203], v[44:47]
	v_mfma_f32_16x16x32_bf16 v[40:43], v[164:167], v[200:203], v[40:43]
	v_mfma_f32_16x16x32_bf16 v[28:31], v[148:151], v[208:211], v[28:31]
	v_mfma_f32_16x16x32_bf16 v[24:27], v[164:167], v[208:211], v[24:27]
	v_mfma_f32_16x16x32_bf16 v[12:15], v[148:151], v[216:219], v[12:15]
	v_mfma_f32_16x16x32_bf16 v[8:11], v[164:167], v[216:219], v[8:11]
.Lwh_p6_2:
	s_setprio 0
	s_setprio 1
	s_cmp_eq_u32 s97, 1
	s_cbranch_scc1 .Lwh_p6_3
	v_mfma_f32_16x16x32_bf16 v[52:55], v[168:171], v[188:191], v[52:55]
	v_mfma_f32_16x16x32_bf16 v[48:51], v[180:183], v[188:191], v[48:51]
	v_mfma_f32_16x16x32_bf16 v[36:39], v[168:171], v[196:199], v[36:39]
	v_mfma_f32_16x16x32_bf16 v[32:35], v[180:183], v[196:199], v[32:35]
	v_mfma_f32_16x16x32_bf16 v[20:23], v[168:171], v[204:207], v[20:23]
	v_mfma_f32_16x16x32_bf16 v[16:19], v[180:183], v[204:207], v[16:19]
	v_mfma_f32_16x16x32_bf16 v[4:7], v[168:171], v[212:215], v[4:7]
	v_mfma_f32_16x16x32_bf16 v[0:3], v[180:183], v[212:215], v[0:3]
	v_mfma_f32_16x16x32_bf16 v[52:55], v[176:179], v[192:195], v[52:55]
	v_mfma_f32_16x16x32_bf16 v[48:51], v[184:187], v[192:195], v[48:51]
	v_mfma_f32_16x16x32_bf16 v[36:39], v[176:179], v[200:203], v[36:39]
	v_mfma_f32_16x16x32_bf16 v[32:35], v[184:187], v[200:203], v[32:35]
	v_mfma_f32_16x16x32_bf16 v[20:23], v[176:179], v[208:211], v[20:23]
	v_mfma_f32_16x16x32_bf16 v[16:19], v[184:187], v[208:211], v[16:19]
	v_mfma_f32_16x16x32_bf16 v[4:7], v[176:179], v[216:219], v[4:7]
	v_mfma_f32_16x16x32_bf16 v[0:3], v[184:187], v[216:219], v[0:3]
.Lwh_p6_3:
	s_setprio 0
	s_barrier
	s_add_i32 s62, 0, 0x18000
	s_add_i32 s63, 0, 0x1c000
	v_add_u32_e32 v164, s62, v153
	v_add_u32_e32 v175, s63, v153
	s_cmp_eq_u32 s97, 1
	s_cbranch_scc1 .Lwhr_p6_3
	ds_read_b128 v[144:147], v164
	ds_read_b128 v[148:151], v164 offset:1024
	ds_read_b128 v[160:163], v164 offset:2048
	ds_read_b128 v[164:167], v164 offset:3072
	ds_read_b128 v[168:171], v175
	ds_read_b128 v[176:179], v175 offset:1024
	ds_read_b128 v[180:183], v175 offset:2048
	ds_read_b128 v[184:187], v175 offset:3072
.Lwhr_p6_3:
	s_add_u32 s42, s42, 0x40000
	s_addc_u32 s43, s43, 0
	s_mov_b32 m0, s47
	v_lshl_add_u64 v[226:227], s[42:43], 0, v[128:129]
	s_cmp_eq_u32 s97, 1
	s_cbranch_scc1 .Lwhr_p6_4
	ds_read_b128 v[188:191], v157 offset:32768
	ds_read_b128 v[192:195], v157 offset:33792
	ds_read_b128 v[196:199], v157 offset:34816
	ds_read_b128 v[200:203], v157 offset:35840
	ds_read_b128 v[204:207], v157 offset:36864
	ds_read_b128 v[208:211], v157 offset:37888
	ds_read_b128 v[212:215], v157 offset:38912
	ds_read_b128 v[216:219], v157 offset:39936
.Lwhr_p6_4:
	global_load_lds_dwordx4 v[226:227], off
	v_lshl_add_u64 v[226:227], s[42:43], 0, v[132:133]
	s_mov_b32 m0, s48
	s_nop 0
	global_load_lds_dwordx4 v[226:227], off
	s_waitcnt vmcnt(8)
	s_waitcnt lgkmcnt(0)
	s_barrier
	s_setprio 1
	s_cmp_eq_u32 s97, 1
	s_cbranch_scc1 .Lwh_p6_4
	s_waitcnt lgkmcnt(0)
	v_mfma_f32_16x16x32_bf16 v[124:127], v[144:147], v[188:191], v[124:127]
	v_mfma_f32_16x16x32_bf16 v[120:123], v[160:163], v[188:191], v[120:123]
	v_mfma_f32_16x16x32_bf16 v[108:111], v[144:147], v[196:199], v[108:111]
	v_mfma_f32_16x16x32_bf16 v[104:107], v[160:163], v[196:199], v[104:107]
	v_mfma_f32_16x16x32_bf16 v[92:95], v[144:147], v[204:207], v[92:95]
	v_mfma_f32_16x16x32_bf16 v[88:91], v[160:163], v[204:207], v[88:91]
	v_mfma_f32_16x16x32_bf16 v[76:79], v[144:147], v[212:215], v[76:79]
	v_mfma_f32_16x16x32_bf16 v[72:75], v[160:163], v[212:215], v[72:75]
	v_mfma_f32_16x16x32_bf16 v[124:127], v[148:151], v[192:195], v[124:127]
	v_mfma_f32_16x16x32_bf16 v[120:123], v[164:167], v[192:195], v[120:123]
	v_mfma_f32_16x16x32_bf16 v[108:111], v[148:151], v[200:203], v[108:111]
	v_mfma_f32_16x16x32_bf16 v[104:107], v[164:167], v[200:203], v[104:107]
	v_mfma_f32_16x16x32_bf16 v[92:95], v[148:151], v[208:211], v[92:95]
	v_mfma_f32_16x16x32_bf16 v[88:91], v[164:167], v[208:211], v[88:91]
	v_mfma_f32_16x16x32_bf16 v[76:79], v[148:151], v[216:219], v[76:79]
	v_mfma_f32_16x16x32_bf16 v[72:75], v[164:167], v[216:219], v[72:75]

.Lwh_p6_5:
	s_setprio 0
	s_barrier
	s_add_i32 s42, s62, s45
	v_lshl_add_u64 v[172:173], v[172:173], 0, s[20:21]
	s_mov_b32 m0, s42
	s_cmp_eq_u32 s97, 1
	s_cbranch_scc1 .Lwhr_p6_5
	ds_read_b128 v[188:191], v157 offset:49152
	ds_read_b128 v[192:195], v157 offset:50176
	ds_read_b128 v[196:199], v157 offset:51200
	ds_read_b128 v[200:203], v157 offset:52224
	ds_read_b128 v[204:207], v157 offset:53248
	ds_read_b128 v[208:211], v157 offset:54272
	ds_read_b128 v[212:215], v157 offset:55296
	ds_read_b128 v[216:219], v157 offset:56320
.Lwhr_p6_5:
	global_load_lds_dwordx4 v[172:173], off
	s_add_i32 m0, s42, 0x2000
	s_add_u32 s40, s40, 0x40080
	v_lshl_add_u64 v[172:173], v[220:221], 0, s[20:21]
	s_addc_u32 s41, s41, 0
	s_add_i32 s42, s63, s45
	global_load_lds_dwordx4 v[172:173], off
	v_lshl_add_u64 v[172:173], s[40:41], 0, v[130:131]
	s_mov_b32 m0, s42
	s_nop 0
	global_load_lds_dwordx4 v[172:173], off
	v_lshl_add_u64 v[172:173], s[40:41], 0, v[134:135]
	s_add_i32 m0, s42, 0x2000
	s_nop 0
	global_load_lds_dwordx4 v[172:173], off
	v_lshl_add_u64 v[172:173], v[222:223], 0, s[20:21]
	s_mov_b32 m0, s50
	s_nop 0
	global_load_lds_dwordx4 v[172:173], off
	v_lshl_add_u64 v[172:173], v[224:225], 0, s[20:21]
	s_mov_b32 m0, s51
	s_nop 0
	global_load_lds_dwordx4 v[172:173], off
	s_waitcnt vmcnt(8)
	s_waitcnt lgkmcnt(0)
	s_barrier
	s_setprio 1
	s_cmp_eq_u32 s97, 1
	s_cbranch_scc1 .Lwh_p6_6
	s_waitcnt lgkmcnt(0)
	v_mfma_f32_16x16x32_bf16 v[60:63], v[144:147], v[188:191], v[60:63]
	v_mfma_f32_16x16x32_bf16 v[56:59], v[160:163], v[188:191], v[56:59]
	v_mfma_f32_16x16x32_bf16 v[44:47], v[144:147], v[196:199], v[44:47]
	v_mfma_f32_16x16x32_bf16 v[40:43], v[160:163], v[196:199], v[40:43]
	v_mfma_f32_16x16x32_bf16 v[28:31], v[144:147], v[204:207], v[28:31]
	v_mfma_f32_16x16x32_bf16 v[24:27], v[160:163], v[204:207], v[24:27]
	v_mfma_f32_16x16x32_bf16 v[12:15], v[144:147], v[212:215], v[12:15]
	v_mfma_f32_16x16x32_bf16 v[8:11], v[160:163], v[212:215], v[8:11]
	v_mfma_f32_16x16x32_bf16 v[60:63], v[148:151], v[192:195], v[60:63]
	v_mfma_f32_16x16x32_bf16 v[56:59], v[164:167], v[192:195], v[56:59]
	v_mfma_f32_16x16x32_bf16 v[44:47], v[148:151], v[200:203], v[44:47]
	v_mfma_f32_16x16x32_bf16 v[40:43], v[164:167], v[200:203], v[40:43]
	v_mfma_f32_16x16x32_bf16 v[28:31], v[148:151], v[208:211], v[28:31]
	v_mfma_f32_16x16x32_bf16 v[24:27], v[164:167], v[208:211], v[24:27]
	v_mfma_f32_16x16x32_bf16 v[12:15], v[148:151], v[216:219], v[12:15]
	v_mfma_f32_16x16x32_bf16 v[8:11], v[164:167], v[216:219], v[8:11]

.Lwh_p6_7:
	s_setprio 0
	s_barrier
	s_add_i32 s61, s61, 2
	s_add_u32 s38, s38, 0x100
	s_addc_u32 s39, s39, 0
	s_add_u32 s59, s59, 0x100
	s_addc_u32 s60, s60, 0
	s_cmp_gt_u32 s61, 13
	s_cbranch_scc0 .LBB0_2040
	s_and_b64 vcc, exec, s[22:23]
	s_cbranch_vccz .LBB0_2043
	s_barrier
.LBB0_2043:
	s_cmp_eq_u32 s97, 1
	s_cbranch_scc1 .Lwh_p6_epi
	v_lshl_add_u32 v146, s36, 8, v152
	v_ashrrev_i32_e32 v147, 31, v146
	v_lshl_add_u64 v[148:149], v[146:147], 3, s[18:19]
	v_lshl_or_b32 v144, s34, 8, v154
	global_load_dwordx2 v[172:173], v[148:149], off
	v_lshlrev_b64 v[150:151], 11, v[146:147]
	v_lshl_add_u64 v[150:151], s[12:13], 0, v[150:151]
	v_ashrrev_i32_e32 v145, 31, v144
	v_lshl_add_u64 v[176:177], v[144:145], 1, v[150:151]
	global_load_dwordx4 v[160:163], v[176:177], off
	v_lshlrev_b64 v[150:151], 12, v[146:147]
	v_lshl_add_u64 v[150:151], s[16:17], 0, v[150:151]
	v_lshl_add_u64 v[150:151], v[144:145], 2, v[150:151]
	global_load_dwordx4 v[164:167], v[150:151], off
	global_load_dwordx4 v[168:171], v[150:151], off offset:16
	s_waitcnt vmcnt(0)
	v_ffbh_u32_e32 v175, v173
	v_min_u32_e32 v175, 32, v175
	v_lshlrev_b64 v[172:173], v175, v[172:173]
	v_sub_u32_e32 v175, 32, v175
	v_lshlrev_b32_e32 v178, 16, v160
	v_and_b32_e32 v179, 0xffff0000, v160
	v_min_u32_e32 v160, 1, v172
	v_or_b32_e32 v160, v173, v160
	v_cvt_f32_u32_e32 v160, v160
	v_lshlrev_b32_e32 v172, 16, v162
	v_and_b32_e32 v173, 0xffff0000, v162
	v_lshlrev_b32_e32 v180, 16, v161
	v_ldexp_f32 v160, v160, v175
	v_fmamk_f32 v160, v160, 0x30800000, v159
	v_mul_f32_e32 v162, 0x4b800000, v160
	v_cmp_gt_f32_e32 vcc, s57, v160
	v_and_b32_e32 v181, 0xffff0000, v161
	s_nop 0
	v_cndmask_b32_e32 v160, v160, v162, vcc
	v_rsq_f32_e32 v160, v160
	v_lshlrev_b32_e32 v162, 16, v163
	v_and_b32_e32 v163, 0xffff0000, v163
	v_mul_f32_e32 v161, 0x45800000, v160
	v_cndmask_b32_e32 v175, v160, v161, vcc
	v_mul_f32_e64 v124, v124, -v175
	v_mul_f32_e64 v120, v120, -v175
	v_mul_f32_e64 v125, v125, -v175
	v_mul_f32_e64 v121, v121, -v175
	v_mul_f32_e64 v126, v126, -v175
	v_mul_f32_e64 v127, v127, -v175
	v_mul_f32_e64 v122, v122, -v175
	v_mul_f32_e64 v123, v123, -v175
	v_mul_f32_e32 v124, 0x3fb8aa3b, v124
	v_mul_f32_e32 v120, 0x3fb8aa3b, v120
	v_mul_f32_e32 v125, 0x3fb8aa3b, v125
	v_mul_f32_e32 v121, 0x3fb8aa3b, v121
	v_mul_f32_e32 v126, 0x3fb8aa3b, v126
	v_mul_f32_e32 v127, 0x3fb8aa3b, v127
	v_mul_f32_e32 v122, 0x3fb8aa3b, v122
	v_mul_f32_e32 v123, 0x3fb8aa3b, v123
	v_exp_f32_e32 v124, v124
	v_exp_f32_e32 v120, v120
	v_exp_f32_e32 v125, v125
	v_exp_f32_e32 v121, v121
	v_exp_f32_e32 v126, v126
	v_exp_f32_e32 v127, v127
	v_exp_f32_e32 v122, v122
	v_exp_f32_e32 v123, v123
	v_add_f32_e32 v124, 1.0, v124
	v_add_f32_e32 v160, 1.0, v120
	v_add_f32_e32 v125, 1.0, v125
	v_add_f32_e32 v161, 1.0, v121
	v_add_f32_e32 v126, 1.0, v126
	v_add_f32_e32 v127, 1.0, v127
	v_add_f32_e32 v122, 1.0, v122
	v_add_f32_e32 v123, 1.0, v123
	v_rcp_f32_e32 v120, v124
	v_rcp_f32_e32 v124, v160
	v_rcp_f32_e32 v121, v125
	v_rcp_f32_e32 v125, v161
	v_rcp_f32_e32 v126, v126
	v_rcp_f32_e32 v127, v127
	v_rcp_f32_e32 v182, v122
	v_rcp_f32_e32 v183, v123
	v_pk_fma_f32 v[122:123], v[120:121], v[178:179], v[164:165]
	v_pk_fma_f32 v[160:161], v[124:125], v[172:173], v[168:169]
	v_pk_fma_f32 v[124:125], v[126:127], v[180:181], v[166:167]
	v_pk_fma_f32 v[162:163], v[182:183], v[162:163], v[170:171]
	global_store_dwordx4 v[150:151], v[122:125], off
	global_store_dwordx4 v[150:151], v[160:163], off offset:16
	global_load_dwordx4 v[164:167], v[176:177], off offset:256
	global_load_dwordx4 v[168:171], v[150:151], off offset:512
	s_nop 0
	global_load_dwordx4 v[176:179], v[150:151], off offset:528
	v_mul_f32_e64 v116, v116, -v175
	v_mul_f32_e64 v112, v112, -v175
	v_mul_f32_e64 v117, v117, -v175
	v_mul_f32_e64 v113, v113, -v175
	v_mul_f32_e64 v118, v118, -v175
	v_mul_f32_e64 v114, v114, -v175
	v_mul_f32_e64 v119, v119, -v175
	v_mul_f32_e64 v115, v115, -v175
	v_mul_f32_e32 v116, 0x3fb8aa3b, v116
	v_mul_f32_e32 v112, 0x3fb8aa3b, v112
	v_mul_f32_e32 v117, 0x3fb8aa3b, v117
	v_mul_f32_e32 v113, 0x3fb8aa3b, v113
	v_mul_f32_e32 v118, 0x3fb8aa3b, v118
	v_mul_f32_e32 v114, 0x3fb8aa3b, v114
	v_mul_f32_e32 v119, 0x3fb8aa3b, v119
	v_mul_f32_e32 v115, 0x3fb8aa3b, v115
	v_exp_f32_e32 v116, v116
	v_exp_f32_e32 v112, v112
	v_exp_f32_e32 v117, v117
	v_exp_f32_e32 v113, v113
	v_exp_f32_e32 v118, v118
	v_exp_f32_e32 v114, v114
	v_exp_f32_e32 v119, v119
	v_exp_f32_e32 v115, v115
	v_add_f32_e32 v116, 1.0, v116
	v_add_f32_e32 v126, 1.0, v112
	v_add_f32_e32 v117, 1.0, v117
	v_add_f32_e32 v127, 1.0, v113
	v_add_f32_e32 v118, 1.0, v118
	v_add_f32_e32 v172, 1.0, v114
	v_add_f32_e32 v119, 1.0, v119
	v_add_f32_e32 v173, 1.0, v115
	v_rcp_f32_e32 v112, v116
	v_rcp_f32_e32 v114, v126
	v_rcp_f32_e32 v113, v117
	v_rcp_f32_e32 v115, v127
	v_rcp_f32_e32 v116, v118
	v_rcp_f32_e32 v118, v172
	v_rcp_f32_e32 v117, v119
	v_rcp_f32_e32 v119, v173
	v_pk_mul_f32 v[122:123], v[122:123], v[122:123]
	v_pk_mul_f32 v[124:125], v[124:125], v[124:125]
	v_pk_mul_f32 v[126:127], v[160:161], v[160:161]
	v_pk_mul_f32 v[160:161], v[162:163], v[162:163]
	v_add_f32_e32 v126, v126, v127
	v_add_f32_e32 v160, v160, v161
	v_add_f32_e32 v124, v124, v125
	v_add_f32_e32 v122, v122, v123
	v_add_f32_e32 v123, v126, v160
	v_add_f32_e32 v122, v122, v124
	v_add_f32_e32 v172, v122, v123
	v_and_b32_e32 v121, 64, v158
	v_xor_b32_e32 v120, 16, v158
	v_add_u32_e32 v121, 64, v121
	v_cmp_lt_i32_e32 vcc, v120, v121
	s_waitcnt vmcnt(2)
	v_lshlrev_b32_e32 v122, 16, v164
	v_and_b32_e32 v123, 0xffff0000, v164
	v_lshlrev_b32_e32 v124, 16, v166
	v_and_b32_e32 v125, 0xffff0000, v166
	v_lshlrev_b32_e32 v126, 16, v165
	v_and_b32_e32 v127, 0xffff0000, v165
	v_lshlrev_b32_e32 v162, 16, v167
	v_and_b32_e32 v163, 0xffff0000, v167
	s_waitcnt vmcnt(1)
	v_pk_fma_f32 v[122:123], v[112:113], v[122:123], v[168:169]
	s_waitcnt vmcnt(0)
	v_pk_fma_f32 v[160:161], v[114:115], v[124:125], v[176:177]
	v_pk_fma_f32 v[124:125], v[116:117], v[126:127], v[170:171]
	v_pk_fma_f32 v[162:163], v[118:119], v[162:163], v[178:179]
	v_pk_mul_f32 v[112:113], v[122:123], v[122:123]
	v_pk_mul_f32 v[114:115], v[124:125], v[124:125]
	v_pk_mul_f32 v[116:117], v[160:161], v[160:161]
	v_pk_mul_f32 v[118:119], v[162:163], v[162:163]
	v_add_f32_e32 v116, v116, v117
	v_add_f32_e32 v118, v118, v119
	v_add_f32_e32 v114, v114, v115
	v_add_f32_e32 v112, v112, v113
	v_add_f32_e32 v113, v116, v118
	v_add_f32_e32 v112, v112, v114
	v_cndmask_b32_e32 v120, v158, v120, vcc
	v_add_f32_e32 v112, v112, v113
	v_lshlrev_b32_e32 v120, 2, v120
	v_add_f32_e32 v112, v172, v112
	ds_bpermute_b32 v113, v120, v112
	v_xor_b32_e32 v114, 32, v158
	v_cmp_lt_i32_e32 vcc, v114, v121
	global_store_dwordx4 v[150:151], v[122:125], off offset:512
	global_store_dwordx4 v[150:151], v[160:163], off offset:528
	v_cndmask_b32_e32 v114, v158, v114, vcc
	v_lshlrev_b32_e32 v116, 2, v114
	s_waitcnt lgkmcnt(0)
	v_add_f32_e32 v112, v112, v113
	ds_bpermute_b32 v113, v116, v112
	s_and_saveexec_b64 s[34:35], s[6:7]
	s_cbranch_execz .LBB0_2045
	s_waitcnt lgkmcnt(0)
	v_add_f32_e32 v112, v112, v113
	v_mul_f32_e32 v112, 0x49800000, v112
	v_trunc_f32_e32 v112, v112
	v_mul_f32_e32 v113, 0x2f800000, v112
	v_floor_f32_e32 v113, v113
	v_fmac_f32_e32 v112, 0xcf800000, v113
	v_cvt_u32_f32_e32 v112, v112
	v_cvt_u32_f32_e32 v113, v113
	v_lshl_add_u64 v[114:115], v[146:147], 3, s[14:15]
	global_atomic_add_x2 v[114:115], v[112:113], off

.Lwh_p6_epi:
	s_andn2_b64 vcc, exec, s[8:9]
	s_mov_b64 s[8:9], -1
	s_cbranch_vccnz .LBB0_2036
	s_andn2_b64 vcc, exec, s[10:11]
	s_cbranch_vccnz .LBB0_2035
	s_barrier
	s_branch .LBB0_2035
